# EPI_RES GEMM epilogues (w_out and ffn_down residual add): residual loads batched 8 at a time with counted vmcnt instead of 32 serialized load-wait-store round trips
# speedup vs baseline: 1.0207x; 1.0121x over previous
; #define UFOR(v, n) _Pragma("unroll") for (int v = 0; v < (n); ++v)
; template <int EPI, int K, int KL> ...
;     ...
;   } else if (EPI == EPI_RES) {
;     const float* src; float* dst; const float* gt; long r0 = brow;
;     if (brow < ML) { src = e.srcL; dst = e.dstL; gt = e.gate + (size_t)(brow >> 14) * 12288; }
;     else { src = e.srcC; dst = e.dstC; gt = e.gate + (size_t)2 * 12288; r0 = brow - ML; }
;     UFOR(bj, 2) UFOR(n, 2) {
;       const int c = bcol + bj * HALF + wc * 32 + fq * 8 + n * 4;
;       const float4 gv = *(const float4*)(gt + c);
;       UFOR(ai, 2) {
;         UFOR(m, 4) {
;           const size_t idx = (size_t)(r0 + ai * HALF + wr * 64 + m * 16 + fr) * DM + c;
;           float4 s = *(const float4*)(src + idx);
;           const f32x4 a = acc[ai][bj][m][n];
;           s.x += gv.x * a[0]; s.y += gv.y * a[1]; s.z += gv.z * a[2]; s.w += gv.w * a[3];
;           *(float4*)(dst + idx) = s;
.LBB0_932:
	v_lshlrev_b32_e32 v128, 5, v152
	v_lshlrev_b32_e32 v129, 3, v153
	v_or3_b32 v142, v128, v129, s54
	v_ashrrev_i32_e32 v129, 31, v155
	v_or_b32_e32 v128, v155, v132
	v_lshl_add_u64 v[128:129], v[128:129], 0, s[60:61]
	v_lshlrev_b64 v[150:151], 11, v[128:129]
	v_ashrrev_i32_e32 v143, 31, v142
	v_lshl_add_u64 v[128:129], v[150:151], 0, v[142:143]
	v_lshl_add_u64 v[146:147], v[142:143], 2, s[62:63]
	v_lshlrev_b64 v[128:129], 2, v[128:129]
	v_lshl_add_u64 v[148:149], s[58:59], 0, v[128:129]
	s_waitcnt lgkmcnt(0)
	v_lshl_add_u64 v[144:145], s[56:57], 0, v[128:129]
	global_load_dwordx4 v[156:159], v[146:147], off
	global_load_dwordx4 v[160:163], v[146:147], off offset:16
	global_load_dwordx4 v[164:167], v[146:147], off offset:512
	global_load_dwordx4 v[168:171], v[146:147], off offset:528
	v_mov_b32_e32 v172, v128
	v_add_u32_e32 v173, 0x20000, v172
	v_add_u32_e32 v174, 0x40000, v172
	v_add_u32_e32 v175, 0x60000, v172
	v_add_u32_e32 v176, 0x100000, v172
	v_add_u32_e32 v177, 0x120000, v172
	v_add_u32_e32 v178, 0x140000, v172
	v_add_u32_e32 v179, 0x160000, v172
	global_load_dwordx4 v[208:211], v172, s[58:59]
	global_load_dwordx4 v[212:215], v173, s[58:59]
	global_load_dwordx4 v[216:219], v174, s[58:59]
	global_load_dwordx4 v[220:223], v175, s[58:59]
	global_load_dwordx4 v[224:227], v176, s[58:59]
	global_load_dwordx4 v[228:231], v177, s[58:59]
	global_load_dwordx4 v[232:235], v178, s[58:59]
	global_load_dwordx4 v[236:239], v179, s[58:59]
	global_load_dwordx4 v[180:183], v172, s[58:59] offset:16
	global_load_dwordx4 v[184:187], v173, s[58:59] offset:16
	global_load_dwordx4 v[188:191], v174, s[58:59] offset:16
	global_load_dwordx4 v[192:195], v175, s[58:59] offset:16
	global_load_dwordx4 v[196:199], v176, s[58:59] offset:16
	global_load_dwordx4 v[200:203], v177, s[58:59] offset:16
	global_load_dwordx4 v[240:243], v178, s[58:59] offset:16
	global_load_dwordx4 v[244:247], v179, s[58:59] offset:16
	s_waitcnt vmcnt(8)
	v_pk_fma_f32 v[208:209], v[124:125], v[156:157], v[208:209]
	v_pk_fma_f32 v[210:211], v[126:127], v[158:159], v[210:211]
	global_store_dwordx4 v172, v[208:211], s[56:57]
	v_pk_fma_f32 v[212:213], v[120:121], v[156:157], v[212:213]
	v_pk_fma_f32 v[214:215], v[122:123], v[158:159], v[214:215]
	global_store_dwordx4 v173, v[212:215], s[56:57]
	v_pk_fma_f32 v[216:217], v[116:117], v[156:157], v[216:217]
	v_pk_fma_f32 v[218:219], v[118:119], v[158:159], v[218:219]
	global_store_dwordx4 v174, v[216:219], s[56:57]
	v_pk_fma_f32 v[220:221], v[108:109], v[156:157], v[220:221]
	v_pk_fma_f32 v[222:223], v[110:111], v[158:159], v[222:223]
	global_store_dwordx4 v175, v[220:223], s[56:57]
	v_pk_fma_f32 v[224:225], v[112:113], v[156:157], v[224:225]
	v_pk_fma_f32 v[226:227], v[114:115], v[158:159], v[226:227]
	global_store_dwordx4 v176, v[224:227], s[56:57]
	v_pk_fma_f32 v[228:229], v[104:105], v[156:157], v[228:229]
	v_pk_fma_f32 v[230:231], v[106:107], v[158:159], v[230:231]
	global_store_dwordx4 v177, v[228:231], s[56:57]
	v_pk_fma_f32 v[232:233], v[100:101], v[156:157], v[232:233]
	v_pk_fma_f32 v[234:235], v[102:103], v[158:159], v[234:235]
	global_store_dwordx4 v178, v[232:235], s[56:57]
	v_pk_fma_f32 v[236:237], v[96:97], v[156:157], v[236:237]
	v_pk_fma_f32 v[238:239], v[98:99], v[158:159], v[238:239]
	global_store_dwordx4 v179, v[236:239], s[56:57]
	global_load_dwordx4 v[208:211], v172, s[58:59] offset:512
	global_load_dwordx4 v[212:215], v173, s[58:59] offset:512
	global_load_dwordx4 v[216:219], v174, s[58:59] offset:512
	global_load_dwordx4 v[220:223], v175, s[58:59] offset:512
	global_load_dwordx4 v[224:227], v176, s[58:59] offset:512
	global_load_dwordx4 v[228:231], v177, s[58:59] offset:512
	global_load_dwordx4 v[232:235], v178, s[58:59] offset:512
	global_load_dwordx4 v[236:239], v179, s[58:59] offset:512
	s_waitcnt vmcnt(16)
; #define UFOR(v, n) _Pragma("unroll") for (int v = 0; v < (n); ++v)
; template <int EPI, int K, int KL> ...
;     ...
;     UFOR(bj, 2) UFOR(n, 2) {
;       const int c = bcol + bj * HALF + wc * 32 + fq * 8 + n * 4;
;       const float4 gv = *(const float4*)(gt + c);
;       UFOR(ai, 2) {
;         UFOR(m, 4) {
;           const size_t idx = (size_t)(r0 + ai * HALF + wr * 64 + m * 16 + fr) * DM + c;
;           float4 s = *(const float4*)(src + idx);
;           const f32x4 a = acc[ai][bj][m][n];
;           s.x += gv.x * a[0]; s.y += gv.y * a[1]; s.z += gv.z * a[2]; s.w += gv.w * a[3];
;           *(float4*)(dst + idx) = s;
;         }
;         __builtin_amdgcn_sched_barrier(0);
;       }
;     }
	v_pk_fma_f32 v[180:181], v[92:93], v[160:161], v[180:181]
	v_pk_fma_f32 v[182:183], v[94:95], v[162:163], v[182:183]
	global_store_dwordx4 v172, v[180:183], s[56:57] offset:16
	v_pk_fma_f32 v[184:185], v[88:89], v[160:161], v[184:185]
	v_pk_fma_f32 v[186:187], v[90:91], v[162:163], v[186:187]
	global_store_dwordx4 v173, v[184:187], s[56:57] offset:16
	v_pk_fma_f32 v[188:189], v[84:85], v[160:161], v[188:189]
	v_pk_fma_f32 v[190:191], v[86:87], v[162:163], v[190:191]
	global_store_dwordx4 v174, v[188:191], s[56:57] offset:16
	v_pk_fma_f32 v[192:193], v[76:77], v[160:161], v[192:193]
	v_pk_fma_f32 v[194:195], v[78:79], v[162:163], v[194:195]
	global_store_dwordx4 v175, v[192:195], s[56:57] offset:16
	v_pk_fma_f32 v[196:197], v[80:81], v[160:161], v[196:197]
	v_pk_fma_f32 v[198:199], v[82:83], v[162:163], v[198:199]
	global_store_dwordx4 v176, v[196:199], s[56:57] offset:16
	v_pk_fma_f32 v[200:201], v[72:73], v[160:161], v[200:201]
	v_pk_fma_f32 v[202:203], v[74:75], v[162:163], v[202:203]
	global_store_dwordx4 v177, v[200:203], s[56:57] offset:16
	v_pk_fma_f32 v[240:241], v[68:69], v[160:161], v[240:241]
	v_pk_fma_f32 v[242:243], v[70:71], v[162:163], v[242:243]
	global_store_dwordx4 v178, v[240:243], s[56:57] offset:16
	v_pk_fma_f32 v[244:245], v[64:65], v[160:161], v[244:245]
	v_pk_fma_f32 v[246:247], v[66:67], v[162:163], v[246:247]
	global_store_dwordx4 v179, v[244:247], s[56:57] offset:16
	global_load_dwordx4 v[180:183], v172, s[58:59] offset:528
	global_load_dwordx4 v[184:187], v173, s[58:59] offset:528
	global_load_dwordx4 v[188:191], v174, s[58:59] offset:528
	global_load_dwordx4 v[192:195], v175, s[58:59] offset:528
	global_load_dwordx4 v[196:199], v176, s[58:59] offset:528
	global_load_dwordx4 v[200:203], v177, s[58:59] offset:528
	global_load_dwordx4 v[240:243], v178, s[58:59] offset:528
	global_load_dwordx4 v[244:247], v179, s[58:59] offset:528
	s_waitcnt vmcnt(16)
	v_pk_fma_f32 v[208:209], v[60:61], v[164:165], v[208:209]
	v_pk_fma_f32 v[210:211], v[62:63], v[166:167], v[210:211]
	global_store_dwordx4 v172, v[208:211], s[56:57] offset:512
	v_pk_fma_f32 v[212:213], v[56:57], v[164:165], v[212:213]
	v_pk_fma_f32 v[214:215], v[58:59], v[166:167], v[214:215]
	global_store_dwordx4 v173, v[212:215], s[56:57] offset:512
	v_pk_fma_f32 v[216:217], v[52:53], v[164:165], v[216:217]
	v_pk_fma_f32 v[218:219], v[54:55], v[166:167], v[218:219]
	global_store_dwordx4 v174, v[216:219], s[56:57] offset:512
	v_pk_fma_f32 v[220:221], v[44:45], v[164:165], v[220:221]
	v_pk_fma_f32 v[222:223], v[46:47], v[166:167], v[222:223]
	global_store_dwordx4 v175, v[220:223], s[56:57] offset:512
	v_pk_fma_f32 v[224:225], v[48:49], v[164:165], v[224:225]
	v_pk_fma_f32 v[226:227], v[50:51], v[166:167], v[226:227]
	global_store_dwordx4 v176, v[224:227], s[56:57] offset:512
	v_pk_fma_f32 v[228:229], v[40:41], v[164:165], v[228:229]
	v_pk_fma_f32 v[230:231], v[42:43], v[166:167], v[230:231]
	global_store_dwordx4 v177, v[228:231], s[56:57] offset:512
	v_pk_fma_f32 v[232:233], v[36:37], v[164:165], v[232:233]
	v_pk_fma_f32 v[234:235], v[38:39], v[166:167], v[234:235]
	global_store_dwordx4 v178, v[232:235], s[56:57] offset:512
	v_pk_fma_f32 v[236:237], v[32:33], v[164:165], v[236:237]
	v_pk_fma_f32 v[238:239], v[34:35], v[166:167], v[238:239]
	global_store_dwordx4 v179, v[236:239], s[56:57] offset:512
	s_waitcnt vmcnt(8)
	v_pk_fma_f32 v[180:181], v[28:29], v[168:169], v[180:181]
	v_pk_fma_f32 v[182:183], v[30:31], v[170:171], v[182:183]
	global_store_dwordx4 v172, v[180:183], s[56:57] offset:528
	v_pk_fma_f32 v[184:185], v[24:25], v[168:169], v[184:185]
	v_pk_fma_f32 v[186:187], v[26:27], v[170:171], v[186:187]
	global_store_dwordx4 v173, v[184:187], s[56:57] offset:528
	v_pk_fma_f32 v[188:189], v[20:21], v[168:169], v[188:189]
	v_pk_fma_f32 v[190:191], v[22:23], v[170:171], v[190:191]
	global_store_dwordx4 v174, v[188:191], s[56:57] offset:528
	v_pk_fma_f32 v[192:193], v[12:13], v[168:169], v[192:193]
	v_pk_fma_f32 v[194:195], v[14:15], v[170:171], v[194:195]
	global_store_dwordx4 v175, v[192:195], s[56:57] offset:528
	v_pk_fma_f32 v[196:197], v[16:17], v[168:169], v[196:197]
	v_pk_fma_f32 v[198:199], v[18:19], v[170:171], v[198:199]
	global_store_dwordx4 v176, v[196:199], s[56:57] offset:528
	v_pk_fma_f32 v[200:201], v[8:9], v[168:169], v[200:201]
	v_pk_fma_f32 v[202:203], v[10:11], v[170:171], v[202:203]
	global_store_dwordx4 v177, v[200:203], s[56:57] offset:528
	v_pk_fma_f32 v[240:241], v[4:5], v[168:169], v[240:241]
	v_pk_fma_f32 v[242:243], v[6:7], v[170:171], v[242:243]
	global_store_dwordx4 v178, v[240:243], s[56:57] offset:528
	v_pk_fma_f32 v[244:245], v[0:1], v[168:169], v[244:245]
	v_pk_fma_f32 v[246:247], v[2:3], v[170:171], v[246:247]
	global_store_dwordx4 v179, v[244:247], s[56:57] offset:528
	s_mov_b64 s[58:59], 0
	s_andn2_b64 vcc, exec, s[48:49]
	s_mov_b32 s54, s19
	s_mov_b64 s[52:53], s[50:51]
	s_cbranch_vccz .LBB0_949

; #define UFOR(v, n) _Pragma("unroll") for (int v = 0; v < (n); ++v)
; template <int EPI, int K, int KL> ...
;     ...
;   } else if (EPI == EPI_RES) {
;     const float* src; float* dst; const float* gt; long r0 = brow;
;     if (brow < ML) { src = e.srcL; dst = e.dstL; gt = e.gate + (size_t)(brow >> 14) * 12288; }
;     else { src = e.srcC; dst = e.dstC; gt = e.gate + (size_t)2 * 12288; r0 = brow - ML; }
;     UFOR(bj, 2) UFOR(n, 2) {
;       const int c = bcol + bj * HALF + wc * 32 + fq * 8 + n * 4;
;       const float4 gv = *(const float4*)(gt + c);
;       UFOR(ai, 2) {
;         UFOR(m, 4) {
;           const size_t idx = (size_t)(r0 + ai * HALF + wr * 64 + m * 16 + fr) * DM + c;
;           float4 s = *(const float4*)(src + idx);
;           const f32x4 a = acc[ai][bj][m][n];
;           s.x += gv.x * a[0]; s.y += gv.y * a[1]; s.z += gv.z * a[2]; s.w += gv.w * a[3];
;           *(float4*)(dst + idx) = s;
.LBB0_1176:
	v_lshlrev_b32_e32 v124, 5, v152
	v_lshlrev_b32_e32 v125, 3, v153
	v_or3_b32 v124, v124, v125, s18
	v_ashrrev_i32_e32 v127, 31, v155
	v_or_b32_e32 v126, v155, v132
	v_lshl_add_u64 v[126:127], v[126:127], 0, s[52:53]
	v_ashrrev_i32_e32 v125, 31, v124
	v_lshlrev_b64 v[124:125], 2, v[124:125]
	v_lshlrev_b64 v[126:127], 13, v[126:127]
	v_lshl_add_u64 v[142:143], s[54:55], 0, v[124:125]
	s_waitcnt lgkmcnt(0)
	v_lshl_add_u64 v[126:127], s[50:51], 0, v[126:127]
	v_lshl_add_u64 v[140:141], v[126:127], 0, v[124:125]
	global_load_dwordx4 v[156:159], v[142:143], off
	global_load_dwordx4 v[160:163], v[142:143], off offset:16
	global_load_dwordx4 v[164:167], v[142:143], off offset:512
	global_load_dwordx4 v[168:171], v[142:143], off offset:528
	v_subrev_u32_e32 v172, s50, v140
	v_add_u32_e32 v173, 0x20000, v172
	v_add_u32_e32 v174, 0x40000, v172
	v_add_u32_e32 v175, 0x60000, v172
	v_add_u32_e32 v176, 0x100000, v172
	v_add_u32_e32 v177, 0x120000, v172
	v_add_u32_e32 v178, 0x140000, v172
	v_add_u32_e32 v179, 0x160000, v172
	global_load_dwordx4 v[208:211], v172, s[50:51]
	global_load_dwordx4 v[212:215], v173, s[50:51]
	global_load_dwordx4 v[216:219], v174, s[50:51]
	global_load_dwordx4 v[220:223], v175, s[50:51]
	global_load_dwordx4 v[224:227], v176, s[50:51]
	global_load_dwordx4 v[228:231], v177, s[50:51]
	global_load_dwordx4 v[232:235], v178, s[50:51]
	global_load_dwordx4 v[236:239], v179, s[50:51]
	global_load_dwordx4 v[180:183], v172, s[50:51] offset:16
	global_load_dwordx4 v[184:187], v173, s[50:51] offset:16
	global_load_dwordx4 v[188:191], v174, s[50:51] offset:16
	global_load_dwordx4 v[192:195], v175, s[50:51] offset:16
	global_load_dwordx4 v[196:199], v176, s[50:51] offset:16
	global_load_dwordx4 v[200:203], v177, s[50:51] offset:16
	global_load_dwordx4 v[240:243], v178, s[50:51] offset:16
	global_load_dwordx4 v[244:247], v179, s[50:51] offset:16
	s_waitcnt vmcnt(8)
	v_pk_fma_f32 v[208:209], v[128:129], v[156:157], v[208:209]
	v_pk_fma_f32 v[210:211], v[130:131], v[158:159], v[210:211]
	global_store_dwordx4 v172, v[208:211], s[50:51]
	v_pk_fma_f32 v[212:213], v[120:121], v[156:157], v[212:213]
	v_pk_fma_f32 v[214:215], v[122:123], v[158:159], v[214:215]
	global_store_dwordx4 v173, v[212:215], s[50:51]
	v_pk_fma_f32 v[216:217], v[116:117], v[156:157], v[216:217]
	v_pk_fma_f32 v[218:219], v[118:119], v[158:159], v[218:219]
	global_store_dwordx4 v174, v[216:219], s[50:51]
	v_pk_fma_f32 v[220:221], v[108:109], v[156:157], v[220:221]
	v_pk_fma_f32 v[222:223], v[110:111], v[158:159], v[222:223]
	global_store_dwordx4 v175, v[220:223], s[50:51]
	v_pk_fma_f32 v[224:225], v[112:113], v[156:157], v[224:225]
	v_pk_fma_f32 v[226:227], v[114:115], v[158:159], v[226:227]
	global_store_dwordx4 v176, v[224:227], s[50:51]
	v_pk_fma_f32 v[228:229], v[104:105], v[156:157], v[228:229]
	v_pk_fma_f32 v[230:231], v[106:107], v[158:159], v[230:231]
	global_store_dwordx4 v177, v[228:231], s[50:51]
	v_pk_fma_f32 v[232:233], v[100:101], v[156:157], v[232:233]
	v_pk_fma_f32 v[234:235], v[102:103], v[158:159], v[234:235]
	global_store_dwordx4 v178, v[232:235], s[50:51]
	v_pk_fma_f32 v[236:237], v[96:97], v[156:157], v[236:237]
	v_pk_fma_f32 v[238:239], v[98:99], v[158:159], v[238:239]
	global_store_dwordx4 v179, v[236:239], s[50:51]
	global_load_dwordx4 v[208:211], v172, s[50:51] offset:512
	global_load_dwordx4 v[212:215], v173, s[50:51] offset:512
	global_load_dwordx4 v[216:219], v174, s[50:51] offset:512
	global_load_dwordx4 v[220:223], v175, s[50:51] offset:512
	global_load_dwordx4 v[224:227], v176, s[50:51] offset:512
	global_load_dwordx4 v[228:231], v177, s[50:51] offset:512
	global_load_dwordx4 v[232:235], v178, s[50:51] offset:512
	global_load_dwordx4 v[236:239], v179, s[50:51] offset:512
	s_waitcnt vmcnt(16)
; #define UFOR(v, n) _Pragma("unroll") for (int v = 0; v < (n); ++v)
; template <int EPI, int K, int KL> ...
;     ...
;     UFOR(bj, 2) UFOR(n, 2) {
;       const int c = bcol + bj * HALF + wc * 32 + fq * 8 + n * 4;
;       const float4 gv = *(const float4*)(gt + c);
;       UFOR(ai, 2) {
;         UFOR(m, 4) {
;           const size_t idx = (size_t)(r0 + ai * HALF + wr * 64 + m * 16 + fr) * DM + c;
;           float4 s = *(const float4*)(src + idx);
;           const f32x4 a = acc[ai][bj][m][n];
;           s.x += gv.x * a[0]; s.y += gv.y * a[1]; s.z += gv.z * a[2]; s.w += gv.w * a[3];
;           *(float4*)(dst + idx) = s;
;         }
;         __builtin_amdgcn_sched_barrier(0);
;       }
;     }
	v_pk_fma_f32 v[180:181], v[92:93], v[160:161], v[180:181]
	v_pk_fma_f32 v[182:183], v[94:95], v[162:163], v[182:183]
	global_store_dwordx4 v172, v[180:183], s[50:51] offset:16
	v_pk_fma_f32 v[184:185], v[88:89], v[160:161], v[184:185]
	v_pk_fma_f32 v[186:187], v[90:91], v[162:163], v[186:187]
	global_store_dwordx4 v173, v[184:187], s[50:51] offset:16
	v_pk_fma_f32 v[188:189], v[84:85], v[160:161], v[188:189]
	v_pk_fma_f32 v[190:191], v[86:87], v[162:163], v[190:191]
	global_store_dwordx4 v174, v[188:191], s[50:51] offset:16
	v_pk_fma_f32 v[192:193], v[72:73], v[160:161], v[192:193]
	v_pk_fma_f32 v[194:195], v[74:75], v[162:163], v[194:195]
	global_store_dwordx4 v175, v[192:195], s[50:51] offset:16
	v_pk_fma_f32 v[196:197], v[80:81], v[160:161], v[196:197]
	v_pk_fma_f32 v[198:199], v[82:83], v[162:163], v[198:199]
	global_store_dwordx4 v176, v[196:199], s[50:51] offset:16
	v_pk_fma_f32 v[200:201], v[76:77], v[160:161], v[200:201]
	v_pk_fma_f32 v[202:203], v[78:79], v[162:163], v[202:203]
	global_store_dwordx4 v177, v[200:203], s[50:51] offset:16
	v_pk_fma_f32 v[240:241], v[68:69], v[160:161], v[240:241]
	v_pk_fma_f32 v[242:243], v[70:71], v[162:163], v[242:243]
	global_store_dwordx4 v178, v[240:243], s[50:51] offset:16
	v_pk_fma_f32 v[244:245], v[64:65], v[160:161], v[244:245]
	v_pk_fma_f32 v[246:247], v[66:67], v[162:163], v[246:247]
	global_store_dwordx4 v179, v[244:247], s[50:51] offset:16
	global_load_dwordx4 v[180:183], v172, s[50:51] offset:528
	global_load_dwordx4 v[184:187], v173, s[50:51] offset:528
	global_load_dwordx4 v[188:191], v174, s[50:51] offset:528
	global_load_dwordx4 v[192:195], v175, s[50:51] offset:528
	global_load_dwordx4 v[196:199], v176, s[50:51] offset:528
	global_load_dwordx4 v[200:203], v177, s[50:51] offset:528
	global_load_dwordx4 v[240:243], v178, s[50:51] offset:528
	global_load_dwordx4 v[244:247], v179, s[50:51] offset:528
	s_waitcnt vmcnt(16)
	v_pk_fma_f32 v[208:209], v[60:61], v[164:165], v[208:209]
	v_pk_fma_f32 v[210:211], v[62:63], v[166:167], v[210:211]
	global_store_dwordx4 v172, v[208:211], s[50:51] offset:512
	v_pk_fma_f32 v[212:213], v[56:57], v[164:165], v[212:213]
	v_pk_fma_f32 v[214:215], v[58:59], v[166:167], v[214:215]
	global_store_dwordx4 v173, v[212:215], s[50:51] offset:512
	v_pk_fma_f32 v[216:217], v[52:53], v[164:165], v[216:217]
	v_pk_fma_f32 v[218:219], v[54:55], v[166:167], v[218:219]
	global_store_dwordx4 v174, v[216:219], s[50:51] offset:512
	v_pk_fma_f32 v[220:221], v[44:45], v[164:165], v[220:221]
	v_pk_fma_f32 v[222:223], v[46:47], v[166:167], v[222:223]
	global_store_dwordx4 v175, v[220:223], s[50:51] offset:512
	v_pk_fma_f32 v[224:225], v[48:49], v[164:165], v[224:225]
	v_pk_fma_f32 v[226:227], v[50:51], v[166:167], v[226:227]
	global_store_dwordx4 v176, v[224:227], s[50:51] offset:512
	v_pk_fma_f32 v[228:229], v[40:41], v[164:165], v[228:229]
	v_pk_fma_f32 v[230:231], v[42:43], v[166:167], v[230:231]
	global_store_dwordx4 v177, v[228:231], s[50:51] offset:512
	v_pk_fma_f32 v[232:233], v[36:37], v[164:165], v[232:233]
	v_pk_fma_f32 v[234:235], v[38:39], v[166:167], v[234:235]
	global_store_dwordx4 v178, v[232:235], s[50:51] offset:512
	v_pk_fma_f32 v[236:237], v[32:33], v[164:165], v[236:237]
	v_pk_fma_f32 v[238:239], v[34:35], v[166:167], v[238:239]
	global_store_dwordx4 v179, v[236:239], s[50:51] offset:512
	s_waitcnt vmcnt(8)
	v_pk_fma_f32 v[180:181], v[28:29], v[168:169], v[180:181]
	v_pk_fma_f32 v[182:183], v[30:31], v[170:171], v[182:183]
	global_store_dwordx4 v172, v[180:183], s[50:51] offset:528
	v_pk_fma_f32 v[184:185], v[24:25], v[168:169], v[184:185]
	v_pk_fma_f32 v[186:187], v[26:27], v[170:171], v[186:187]
	global_store_dwordx4 v173, v[184:187], s[50:51] offset:528
	v_pk_fma_f32 v[188:189], v[20:21], v[168:169], v[188:189]
	v_pk_fma_f32 v[190:191], v[22:23], v[170:171], v[190:191]
	global_store_dwordx4 v174, v[188:191], s[50:51] offset:528
	v_pk_fma_f32 v[192:193], v[12:13], v[168:169], v[192:193]
	v_pk_fma_f32 v[194:195], v[14:15], v[170:171], v[194:195]
	global_store_dwordx4 v175, v[192:195], s[50:51] offset:528
	v_pk_fma_f32 v[196:197], v[16:17], v[168:169], v[196:197]
	v_pk_fma_f32 v[198:199], v[18:19], v[170:171], v[198:199]
	global_store_dwordx4 v176, v[196:199], s[50:51] offset:528
	v_pk_fma_f32 v[200:201], v[8:9], v[168:169], v[200:201]
	v_pk_fma_f32 v[202:203], v[10:11], v[170:171], v[202:203]
	global_store_dwordx4 v177, v[200:203], s[50:51] offset:528
	v_pk_fma_f32 v[240:241], v[4:5], v[168:169], v[240:241]
	v_pk_fma_f32 v[242:243], v[6:7], v[170:171], v[242:243]
	global_store_dwordx4 v178, v[240:243], s[50:51] offset:528
	v_pk_fma_f32 v[244:245], v[0:1], v[168:169], v[244:245]
	v_pk_fma_f32 v[246:247], v[2:3], v[170:171], v[246:247]
	global_store_dwordx4 v179, v[244:247], s[50:51] offset:528
	s_mov_b64 s[52:53], 0
	s_andn2_b64 vcc, exec, s[44:45]
	s_mov_b32 s18, s15
	s_mov_b64 s[48:49], s[46:47]
	s_cbranch_vccz .LBB0_1193
